# attention softmax section hand-scheduled: fma+exp2 interleaved, packed row sums, thresholded O rescale, row-sum exchange deferred to task end
# speedup vs baseline: 1.0098x; 1.0020x over previous
; __device__ __forceinline__ void attn_phase(const Args& a, int layer, LAS unsigned char* lds, int G, int need_ctx) {
;     ...
;             float mx = sc[0];
; #pragma unroll
;             for (int t = 1; t < 16; ++t) mx = fmaxf(mx, sc[t]);
;             mx = fmaxf(mx, __shfl_xor(mx, 32));
;             const float m_new = fmaxf(m_run, mx), alpha = __expf(m_run - m_new);
;             float rs = 0.f;
; #pragma unroll
;             for (int t = 0; t < 16; ++t) { sc[t] = __expf(sc[t] - m_new); rs += sc[t]; }
;             rs += __shfl_xor(rs, 32);
;             l_run = l_run * alpha + rs; m_run = m_new;
;             union { u32x4 u; bf16x8 v; } P0, P1;
;             P0.u.x = pk2(sc[0], sc[1]); P0.u.y = pk2(sc[2], sc[3]); P0.u.z = pk2(sc[4], sc[5]); P0.u.w = pk2(sc[6], sc[7]);
;             P1.u.x = pk2(sc[8], sc[9]); P1.u.y = pk2(sc[10], sc[11]); P1.u.z = pk2(sc[12], sc[13]); P1.u.w = pk2(sc[14], sc[15]);
; #pragma unroll
;             for (int d = 0; d < 4; ++d) {
; #pragma unroll
;                 for (int t = 0; t < 16; ++t) OT[d][t] *= alpha;
;                 OT[d] = __builtin_amdgcn_mfma_f32_32x32x16_bf16(vreg[d * 2 + 0], P0.v, OT[d], 0, 0, 0);
;                 OT[d] = __builtin_amdgcn_mfma_f32_32x32x16_bf16(vreg[d * 2 + 1], P1.v, OT[d], 0, 0, 0);
;             }
;         }
;         const float inv = 1.0f / l_run;
.LBB0_196:
	s_nop 8
	v_max3_f32 v80, v64, v65, v66
	v_max3_f32 v81, v67, v68, v69
	v_max3_f32 v82, v70, v71, v72
	v_max3_f32 v83, v73, v74, v75
	v_max3_f32 v84, v76, v77, v78
	v_max3_f32 v80, v80, v81, v82
	v_max3_f32 v83, v83, v84, v79
	v_max_f32_e32 v80, v80, v83
	ds_bpermute_b32 v81, v235, v80
	s_add_i32 s23, s23, 32
	v_add_u32_e32 v236, 0x7c, v236
	s_mov_b32 s12, 0x3fb8aa3b
	s_waitcnt lgkmcnt(0)
	v_max_f32_e32 v80, v80, v81
	v_max_f32_e32 v81, v238, v80
	v_sub_f32_e32 v82, v81, v238
	v_cmp_lt_f32_e32 vcc, 0x40a00000, v82
	s_nop 1
	v_cndmask_b32_e32 v80, v238, v81, vcc
	v_mul_f32_e32 v83, s12, v80
	v_sub_f32_e32 v84, v238, v80
	v_mul_f32_e32 v87, s12, v80
	v_mul_f32_e32 v84, s12, v84
	v_fma_f32 v64, v64, s12, -v87
	v_fma_f32 v65, v65, s12, -v87
	v_exp_f32_e32 v86, v84
	v_exp_f32_e32 v64, v64
	v_fma_f32 v66, v66, s12, -v87
	v_exp_f32_e32 v65, v65
	v_fma_f32 v67, v67, s12, -v87
	v_exp_f32_e32 v66, v66
	v_fma_f32 v68, v68, s12, -v87
	v_mov_b32_e32 v238, v80
	v_exp_f32_e32 v67, v67
	v_fma_f32 v69, v69, s12, -v87
	v_exp_f32_e32 v68, v68
	v_fma_f32 v70, v70, s12, -v87
	v_exp_f32_e32 v69, v69
	v_fma_f32 v71, v71, s12, -v87
	v_pk_add_f32 v[88:89], v[64:65], v[66:67]
	v_exp_f32_e32 v70, v70
	v_fma_f32 v72, v72, s12, -v87
	v_cvt_pk_bf16_f32 v80, v64, v65
	v_exp_f32_e32 v71, v71
	v_fma_f32 v73, v73, s12, -v87
	v_cvt_pk_bf16_f32 v81, v66, v67
	v_exp_f32_e32 v72, v72
	v_fma_f32 v74, v74, s12, -v87
	v_exp_f32_e32 v73, v73
	v_fma_f32 v75, v75, s12, -v87
	v_pk_add_f32 v[84:85], v[68:69], v[70:71]
	v_exp_f32_e32 v74, v74
	v_fma_f32 v76, v76, s12, -v87
	v_cvt_pk_bf16_f32 v82, v68, v69
	v_exp_f32_e32 v75, v75
	v_fma_f32 v77, v77, s12, -v87
	v_cvt_pk_bf16_f32 v83, v70, v71
	v_exp_f32_e32 v76, v76
	v_fma_f32 v78, v78, s12, -v87
	v_exp_f32_e32 v77, v77
	v_fma_f32 v79, v79, s12, -v87
	v_pk_add_f32 v[90:91], v[72:73], v[74:75]
	v_exp_f32_e32 v78, v78
	v_pk_add_f32 v[88:89], v[88:89], v[84:85]
	v_exp_f32_e32 v79, v79
	v_cvt_pk_bf16_f32 v92, v72, v73
	v_cvt_pk_bf16_f32 v93, v74, v75
	v_pk_add_f32 v[84:85], v[76:77], v[78:79]
	v_pk_add_f32 v[88:89], v[88:89], v[90:91]
	v_cvt_pk_bf16_f32 v94, v76, v77
	v_cvt_pk_bf16_f32 v95, v78, v79
	v_pk_add_f32 v[88:89], v[88:89], v[84:85]
	s_nop 0
	v_add_f32_e32 v88, v88, v89
	v_fma_f32 v237, v237, v86, v88
	s_and_b64 vcc, exec, vcc
	s_cbranch_vccz .Latt_norescale
	v_pk_mul_f32 v[62:63], v[62:63], v[86:87] op_sel_hi:[1,0]
	v_pk_mul_f32 v[60:61], v[60:61], v[86:87] op_sel_hi:[1,0]
	v_pk_mul_f32 v[58:59], v[58:59], v[86:87] op_sel_hi:[1,0]
	v_pk_mul_f32 v[56:57], v[56:57], v[86:87] op_sel_hi:[1,0]
	v_pk_mul_f32 v[54:55], v[54:55], v[86:87] op_sel_hi:[1,0]
	v_pk_mul_f32 v[52:53], v[52:53], v[86:87] op_sel_hi:[1,0]
	v_pk_mul_f32 v[50:51], v[50:51], v[86:87] op_sel_hi:[1,0]
	v_pk_mul_f32 v[48:49], v[48:49], v[86:87] op_sel_hi:[1,0]
	v_pk_mul_f32 v[46:47], v[46:47], v[86:87] op_sel_hi:[1,0]
	v_pk_mul_f32 v[44:45], v[44:45], v[86:87] op_sel_hi:[1,0]
	v_pk_mul_f32 v[42:43], v[42:43], v[86:87] op_sel_hi:[1,0]
	v_pk_mul_f32 v[40:41], v[40:41], v[86:87] op_sel_hi:[1,0]
	v_pk_mul_f32 v[38:39], v[38:39], v[86:87] op_sel_hi:[1,0]
	v_pk_mul_f32 v[36:37], v[36:37], v[86:87] op_sel_hi:[1,0]
	v_pk_mul_f32 v[34:35], v[34:35], v[86:87] op_sel_hi:[1,0]
	v_pk_mul_f32 v[32:33], v[32:33], v[86:87] op_sel_hi:[1,0]
	v_pk_mul_f32 v[30:31], v[30:31], v[86:87] op_sel_hi:[1,0]
	v_pk_mul_f32 v[28:29], v[28:29], v[86:87] op_sel_hi:[1,0]
	v_pk_mul_f32 v[26:27], v[26:27], v[86:87] op_sel_hi:[1,0]
	v_pk_mul_f32 v[24:25], v[24:25], v[86:87] op_sel_hi:[1,0]
	v_pk_mul_f32 v[22:23], v[22:23], v[86:87] op_sel_hi:[1,0]
	v_pk_mul_f32 v[20:21], v[20:21], v[86:87] op_sel_hi:[1,0]
	v_pk_mul_f32 v[18:19], v[18:19], v[86:87] op_sel_hi:[1,0]
	v_pk_mul_f32 v[16:17], v[16:17], v[86:87] op_sel_hi:[1,0]
	v_pk_mul_f32 v[14:15], v[14:15], v[86:87] op_sel_hi:[1,0]
	v_pk_mul_f32 v[12:13], v[12:13], v[86:87] op_sel_hi:[1,0]
	v_pk_mul_f32 v[10:11], v[10:11], v[86:87] op_sel_hi:[1,0]
	v_pk_mul_f32 v[8:9], v[8:9], v[86:87] op_sel_hi:[1,0]
	v_pk_mul_f32 v[6:7], v[6:7], v[86:87] op_sel_hi:[1,0]
	v_pk_mul_f32 v[4:5], v[4:5], v[86:87] op_sel_hi:[1,0]
	v_pk_mul_f32 v[2:3], v[2:3], v[86:87] op_sel_hi:[1,0]
	v_pk_mul_f32 v[0:1], v[0:1], v[86:87] op_sel_hi:[1,0]
.Latt_norescale:
	s_waitcnt vmcnt(7)
	v_mfma_f32_32x32x16_bf16 v[48:63], v[190:193], v[80:83], v[48:63]
	s_waitcnt vmcnt(5)
	v_mfma_f32_32x32x16_bf16 v[32:47], v[182:185], v[80:83], v[32:47]
	s_waitcnt vmcnt(3)
	v_mfma_f32_32x32x16_bf16 v[16:31], v[174:177], v[80:83], v[16:31]
	s_waitcnt vmcnt(1)
	v_mfma_f32_32x32x16_bf16 v[0:15], v[166:169], v[80:83], v[0:15]
	v_mfma_f32_32x32x16_bf16 v[48:63], v[186:189], v[92:95], v[48:63]
	v_mfma_f32_32x32x16_bf16 v[32:47], v[178:181], v[92:95], v[32:47]
	v_mfma_f32_32x32x16_bf16 v[16:31], v[170:173], v[92:95], v[16:31]
	s_waitcnt vmcnt(0)
	v_mfma_f32_32x32x16_bf16 v[0:15], v[162:165], v[92:95], v[0:15]
	s_cmp_eq_u32 s25, s26
	s_cbranch_scc1 .LBB0_198
	s_mov_b32 s27, s26
	s_branch .LBB0_154
.LBB0_198:
	ds_bpermute_b32 v81, v235, v237
	s_waitcnt lgkmcnt(0)
	v_add_f32_e32 v64, v237, v81
	v_readlane_b32 s94, v250, 12
	v_readlane_b32 s92, v251, 49
	v_readlane_b32 s95, v250, 13
